# attention fast loop with 3 K-fragment buffers (prefetch distance 2) on the v15 stack
# baseline (speedup 1.0000x reference)
; __device__ __forceinline__ void finishSM_fix(f32x16& p0, f32x16& p1, float& l_lane, bf16x8& pa0, bf16x8& pa1, bf16x8& pa2, bf16x8& pa3) {
; #pragma unroll
;   for (int r = 0; r < 16; ++r) p1[r] = __builtin_amdgcn_exp2f(p1[r]);
;   float ps = 0;
; #pragma unroll
;   for (int r = 0; r < 16; ++r) ps += p0[r];
; #pragma unroll
;   for (int r = 0; r < 16; ++r) ps += p1[r];
;   l_lane += ps;
;     ...
;   PK4(p0, 0, pa0); PK4(p0, 8, pa1); PK4(p1, 0, pa2); PK4(p1, 8, pa3);
;     ...
; }
; __device__ __forceinline__ void qkt12(f32x16& p0, f32x16& p1, const char* Ks, const bf16x8 (&qr)[12], const int (&kb)[4]) {
;   p0 = f32x16{}; p1 = f32x16{};
;     ...
;   bf16x8 c0 = KLD(0, 0), c1 = KLD(0, 1);
; #pragma unroll
;   for (int d0 = 0; d0 < 12; ++d0) {
;     bf16x8 n0 = c0, n1 = c1;
;     if (d0 < 11) { n0 = KLD(d0 + 1, 0); n1 = KLD(d0 + 1, 1); }
;     __builtin_amdgcn_sched_group_barrier(0x100, 2, 0);
;     p0 = __builtin_amdgcn_mfma_f32_32x32x16_bf16(c0, qr[d0], p0, 0, 0, 0);
;     p1 = __builtin_amdgcn_mfma_f32_32x32x16_bf16(c1, qr[d0], p1, 0, 0, 0);
;     __builtin_amdgcn_sched_group_barrier(0x008, 2, 0);
;     c0 = n0; c1 = n1; }
;     ...
; }
.Lfa_loop:
	s_add_i32 s22, s26, 1
	s_cmp_lg_u32 s26, 2
	s_cselect_b32 s24, s22, 0
	s_add_i32 s22, s24, 1
	s_cmp_lg_u32 s24, 2
	s_cselect_b32 s25, s22, 0
	s_waitcnt vmcnt(5)
	s_barrier
	s_mul_i32 s6, s24, 0x6000
	s_mul_i32 s10, s26, 0x6000
	s_lshl_b32 s11, s25, 14
	s_add_i32 s10, s43, s10
	s_add_i32 s11, s52, s11
	v_add_u32_e32 v187, s6, v183
	v_add_u32_e32 v188, s6, v184
	v_add_u32_e32 v189, s6, v185
	v_add_u32_e32 v190, s6, v186
	v_lshl_add_u32 v191, s26, 14, v182
	ds_read_b128 v[172:175], v187
	ds_read_b128 v[176:179], v187 offset:12288
	ds_read_b128 v[200:203], v188
	ds_read_b128 v[204:207], v188 offset:12288
	ds_read_b128 v[208:211], v189
	ds_read_b128 v[194:197], v189 offset:12288
	v_add_f32_e32 v198, v82, v83
	v_cvt_pk_bf16_f32 v82, v82, v83
	v_add_f32_e32 v199, v84, v85
	v_exp_f32_e32 v66, v66
	v_exp_f32_e32 v67, v67
	v_cvt_pk_bf16_f32 v83, v84, v85
	v_add_f32_e32 v198, v86, v198
	v_add_f32_e32 v199, v87, v199
	s_waitcnt lgkmcnt(5)
	v_mfma_f32_32x32x16_bf16 v[98:113], v[172:175], v[116:119], 0
	v_exp_f32_e32 v68, v68
	v_exp_f32_e32 v69, v69
	s_waitcnt lgkmcnt(4)
	v_mfma_f32_32x32x16_bf16 v[212:227], v[176:179], v[116:119], 0
	ds_read_b128 v[172:175], v190
	ds_read_b128 v[176:179], v190 offset:12288
	v_cvt_pk_bf16_f32 v84, v86, v87
	v_add_f32_e32 v198, v88, v198
	v_add_f32_e32 v199, v89, v199
	v_exp_f32_e32 v70, v70
	s_waitcnt lgkmcnt(5)
	v_mfma_f32_32x32x16_bf16 v[98:113], v[200:203], v[120:123], v[98:113]
	s_mov_b32 m0, s10
	v_lshl_add_u64 v[192:193], v[166:167], 0, s[92:93]
	global_load_lds_dwordx4 v[192:193], off
	v_exp_f32_e32 v71, v71
	s_waitcnt lgkmcnt(4)
	v_mfma_f32_32x32x16_bf16 v[212:227], v[204:207], v[120:123], v[212:227]
	ds_read_b128 v[200:203], v187 offset:128
	ds_read_b128 v[204:207], v187 offset:12416
	v_cvt_pk_bf16_f32 v85, v88, v89
	v_add_f32_e32 v198, v90, v198
	v_add_f32_e32 v199, v91, v199
	v_exp_f32_e32 v72, v72
	s_waitcnt lgkmcnt(5)
	v_mfma_f32_32x32x16_bf16 v[98:113], v[208:211], v[124:127], v[98:113]
	v_exp_f32_e32 v73, v73
	s_waitcnt lgkmcnt(4)
	v_mfma_f32_32x32x16_bf16 v[212:227], v[194:197], v[124:127], v[212:227]
	ds_read_b128 v[208:211], v188 offset:128
	ds_read_b128 v[194:197], v188 offset:12416
	v_cvt_pk_bf16_f32 v86, v90, v91
	v_add_f32_e32 v198, v92, v198
	v_add_f32_e32 v199, v93, v199
	v_exp_f32_e32 v74, v74
	s_waitcnt lgkmcnt(5)
	v_mfma_f32_32x32x16_bf16 v[98:113], v[172:175], v[128:131], v[98:113]
	s_add_i32 m0, s10, 0x400
	v_lshl_add_u64 v[192:193], v[168:169], 0, s[92:93]
	global_load_lds_dwordx4 v[192:193], off
	v_exp_f32_e32 v75, v75
	v_cvt_pk_bf16_f32 v87, v92, v93
	s_waitcnt lgkmcnt(4)
	v_mfma_f32_32x32x16_bf16 v[212:227], v[176:179], v[128:131], v[212:227]
	ds_read_b128 v[172:175], v189 offset:128
	ds_read_b128 v[176:179], v189 offset:12416
	v_add_f32_e32 v198, v94, v198
	v_add_f32_e32 v199, v95, v199
	v_exp_f32_e32 v76, v76
	s_waitcnt lgkmcnt(5)
	v_mfma_f32_32x32x16_bf16 v[98:113], v[200:203], v[132:135], v[98:113]
	v_exp_f32_e32 v77, v77
	v_cvt_pk_bf16_f32 v88, v94, v95
	s_waitcnt lgkmcnt(4)
	v_mfma_f32_32x32x16_bf16 v[212:227], v[204:207], v[132:135], v[212:227]
	ds_read_b128 v[200:203], v190 offset:128
	ds_read_b128 v[204:207], v190 offset:12416
	v_add_f32_e32 v198, v96, v198
	v_add_f32_e32 v199, v97, v199
	v_exp_f32_e32 v78, v78
	s_waitcnt lgkmcnt(5)
	v_mfma_f32_32x32x16_bf16 v[98:113], v[208:211], v[136:139], v[98:113]
	s_add_i32 m0, s10, 0x800
	v_lshl_add_u64 v[192:193], v[170:171], 0, s[92:93]
	global_load_lds_dwordx4 v[192:193], off
	v_exp_f32_e32 v79, v79
	v_cvt_pk_bf16_f32 v89, v96, v97
	s_waitcnt lgkmcnt(4)
	v_mfma_f32_32x32x16_bf16 v[212:227], v[194:197], v[136:139], v[212:227]
	ds_read_b128 v[208:211], v187 offset:256
	ds_read_b128 v[194:197], v187 offset:12544
	v_exp_f32_e32 v80, v80
	v_exp_f32_e32 v81, v81
	s_waitcnt lgkmcnt(5)
	v_mfma_f32_32x32x16_bf16 v[98:113], v[172:175], v[140:143], v[98:113]
	v_add_f32_e32 v198, v66, v198
	v_add_f32_e32 v199, v67, v199
	v_cvt_pk_bf16_f32 v66, v66, v67
	s_waitcnt lgkmcnt(4)
	v_mfma_f32_32x32x16_bf16 v[212:227], v[176:179], v[140:143], v[212:227]
	ds_read_b128 v[172:175], v188 offset:256
	ds_read_b128 v[176:179], v188 offset:12544
	v_permlane32_swap_b32_e32 v82, v84
	v_permlane32_swap_b32_e32 v83, v85
	v_permlane32_swap_b32_e32 v86, v88
	v_permlane32_swap_b32_e32 v87, v89
	s_waitcnt lgkmcnt(5)
	v_mfma_f32_32x32x16_bf16 v[98:113], v[200:203], v[144:147], v[98:113]
	s_mov_b64 s[22:23], 0x61e0c100
	s_mov_b32 m0, s11
	v_lshl_add_u64 v[192:193], v[164:165], 0, s[22:23]
	global_load_lds_dwordx4 v[192:193], off
	v_add_f32_e32 v198, v68, v198
	v_add_f32_e32 v199, v69, v199
	v_cvt_pk_bf16_f32 v67, v68, v69
	s_waitcnt lgkmcnt(4)
	v_mfma_f32_32x32x16_bf16 v[212:227], v[204:207], v[144:147], v[212:227]
	ds_read_b128 v[200:203], v189 offset:256
	ds_read_b128 v[204:207], v189 offset:12544
	v_add_f32_e32 v198, v70, v198
	v_add_f32_e32 v199, v71, v199
	v_cvt_pk_bf16_f32 v68, v70, v71
	v_add_f32_e32 v198, v72, v198
	s_waitcnt lgkmcnt(5)
	v_mfma_f32_32x32x16_bf16 v[98:113], v[208:211], v[152:155], v[98:113]
	ds_read_b64_tr_b16 v[228:229], v191 offset:0
	ds_read_b64_tr_b16 v[230:231], v191 offset:2048
	v_add_f32_e32 v199, v73, v199
	v_cvt_pk_bf16_f32 v69, v72, v73
	v_add_f32_e32 v198, v74, v198
	v_add_f32_e32 v199, v75, v199
	s_waitcnt lgkmcnt(6)
	v_mfma_f32_32x32x16_bf16 v[212:227], v[194:197], v[152:155], v[212:227]
	ds_read_b128 v[208:211], v190 offset:256
	ds_read_b128 v[194:197], v190 offset:12544
	ds_read_b64_tr_b16 v[232:233], v191 offset:4096
	ds_read_b64_tr_b16 v[234:235], v191 offset:6144
	v_cvt_pk_bf16_f32 v70, v74, v75
	v_add_f32_e32 v198, v76, v198
	v_add_f32_e32 v199, v77, v199
	s_waitcnt lgkmcnt(9)
; #define SBAR() __builtin_amdgcn_sched_barrier(0)
; __device__ __forceinline__ void partialSM_fix(f32x16& p0, f32x16& p1) {
; #pragma unroll
;   for (int r = 0; r < 16; ++r) p0[r] = __builtin_amdgcn_exp2f(p0[r]);
; }
; template <int D0> __device__ __forceinline__ void pv_one(f32x16& od, int vb, bf16x8 pa0, bf16x8 pa1, bf16x8 pa2, bf16x8 pa3) {
;   const s16x4 l0 = tr_read<v_rd_off(D0, 0, 0)>(vb), h0 = tr_read<v_rd_off(D0, 0, 1)>(vb), l1 = tr_read<v_rd_off(D0, 1, 0)>(vb), h1 = tr_read<v_rd_off(D0, 1, 1)>(vb);
;   const s16x4 l2 = tr_read<v_rd_off(D0, 2, 0)>(vb), h2 = tr_read<v_rd_off(D0, 2, 1)>(vb), l3 = tr_read<v_rd_off(D0, 3, 0)>(vb), h3 = tr_read<v_rd_off(D0, 3, 1)>(vb);
;   asm volatile("s_waitcnt lgkmcnt(0)" ::: "memory"); SBAR();
;     ...
;   od = __builtin_amdgcn_mfma_f32_32x32x16_bf16(pa0, PK(l0, h0), od, 0, 0, 0);
;   od = __builtin_amdgcn_mfma_f32_32x32x16_bf16(pa1, PK(l1, h1), od, 0, 0, 0);
;   od = __builtin_amdgcn_mfma_f32_32x32x16_bf16(pa2, PK(l2, h2), od, 0, 0, 0);
;   od = __builtin_amdgcn_mfma_f32_32x32x16_bf16(pa3, PK(l3, h3), od, 0, 0, 0);
;     ...
; }
; __device__ __forceinline__ void pv_d0(f32x16 (&o)[4], int vb, bf16x8 pa0, bf16x8 pa1, bf16x8 pa2, bf16x8 pa3) {
;   pv_one<0>(o[0], vb, pa0, pa1, pa2, pa3); pv_one<1>(o[1], vb, pa0, pa1, pa2, pa3); pv_one<2>(o[2], vb, pa0, pa1, pa2, pa3); pv_one<3>(o[3], vb, pa0, pa1, pa2, pa3);
	v_mfma_f32_32x32x16_bf16 v[98:113], v[172:175], v[148:151], v[98:113]
	ds_read_b64_tr_b16 v[236:237], v191 offset:8192
	ds_read_b64_tr_b16 v[238:239], v191 offset:10240
	s_mov_b64 s[22:23], 0x61e0c180
	s_add_i32 m0, s11, 0x400
	v_lshl_add_u64 v[192:193], v[164:165], 0, s[22:23]
	global_load_lds_dwordx4 v[192:193], off
	v_cvt_pk_bf16_f32 v71, v76, v77
	v_add_f32_e32 v198, v78, v198
	v_add_f32_e32 v199, v79, v199
	v_cvt_pk_bf16_f32 v72, v78, v79
	s_waitcnt lgkmcnt(10)
	v_mfma_f32_32x32x16_bf16 v[212:227], v[176:179], v[148:151], v[212:227]
	ds_read_b64_tr_b16 v[240:241], v191 offset:12288
	ds_read_b64_tr_b16 v[242:243], v191 offset:14336
	v_add_f32_e32 v198, v80, v198
	v_add_f32_e32 v199, v81, v199
	v_cvt_pk_bf16_f32 v73, v80, v81
	s_waitcnt lgkmcnt(11)
	v_mfma_f32_32x32x16_bf16 v[98:113], v[200:203], v[160:163], v[98:113]
	ds_read_b64_tr_b16 v[246:247], v191 offset:512
	ds_read_b64_tr_b16 v[248:249], v191 offset:2560
	v_add_f32_e32 v198, v198, v199
	s_nop 0
	v_permlane32_swap_b32_e32 v66, v68
	v_permlane32_swap_b32_e32 v67, v69
	s_waitcnt lgkmcnt(12)
	v_mfma_f32_32x32x16_bf16 v[212:227], v[204:207], v[160:163], v[212:227]
	ds_read_b64_tr_b16 v[250:251], v191 offset:4608
	ds_read_b64_tr_b16 v[252:253], v191 offset:6656
	v_permlane32_swap_b32_e32 v70, v72
	v_permlane32_swap_b32_e32 v71, v73
	v_add_f32_e32 v114, v114, v198
	s_waitcnt lgkmcnt(11)
	v_mfma_f32_32x32x16_bf16 v[98:113], v[208:211], v[156:159], v[98:113]
	s_waitcnt lgkmcnt(10)
	v_mfma_f32_32x32x16_bf16 v[212:227], v[194:197], v[156:159], v[212:227]
	v_mfma_f32_32x32x16_bf16 v[2:17], v[82:85], v[228:231], v[2:17]
	ds_read_b64_tr_b16 v[228:229], v191 offset:8704
	ds_read_b64_tr_b16 v[230:231], v191 offset:10752
	s_waitcnt lgkmcnt(10)
	v_mfma_f32_32x32x16_bf16 v[2:17], v[86:89], v[232:235], v[2:17]
	ds_read_b64_tr_b16 v[232:233], v191 offset:12800
	ds_read_b64_tr_b16 v[234:235], v191 offset:14848
	s_waitcnt lgkmcnt(10)
	v_mfma_f32_32x32x16_bf16 v[2:17], v[66:69], v[236:239], v[2:17]
	ds_read_b64_tr_b16 v[236:237], v191 offset:1024
	ds_read_b64_tr_b16 v[238:239], v191 offset:3072
	s_waitcnt lgkmcnt(10)
	v_mfma_f32_32x32x16_bf16 v[2:17], v[70:73], v[240:243], v[2:17]
	ds_read_b64_tr_b16 v[240:241], v191 offset:5120
	ds_read_b64_tr_b16 v[242:243], v191 offset:7168
	v_exp_f32_e32 v98, v98
	s_waitcnt lgkmcnt(10)
	v_mfma_f32_32x32x16_bf16 v[18:33], v[82:85], v[246:249], v[18:33]
	ds_read_b64_tr_b16 v[246:247], v191 offset:9216
	ds_read_b64_tr_b16 v[248:249], v191 offset:11264
	v_exp_f32_e32 v99, v99
	s_waitcnt lgkmcnt(10)
	v_mfma_f32_32x32x16_bf16 v[18:33], v[86:89], v[250:253], v[18:33]
	ds_read_b64_tr_b16 v[250:251], v191 offset:13312
	ds_read_b64_tr_b16 v[252:253], v191 offset:15360
	v_exp_f32_e32 v100, v100
	s_waitcnt lgkmcnt(10)
	v_mfma_f32_32x32x16_bf16 v[18:33], v[66:69], v[228:231], v[18:33]
	ds_read_b64_tr_b16 v[228:229], v191 offset:1536
	ds_read_b64_tr_b16 v[230:231], v191 offset:3584
	v_exp_f32_e32 v101, v101
	s_waitcnt lgkmcnt(10)
	v_mfma_f32_32x32x16_bf16 v[18:33], v[70:73], v[232:235], v[18:33]
	ds_read_b64_tr_b16 v[232:233], v191 offset:5632
	ds_read_b64_tr_b16 v[234:235], v191 offset:7680
	v_exp_f32_e32 v102, v102
	s_waitcnt lgkmcnt(10)
	v_mfma_f32_32x32x16_bf16 v[34:49], v[82:85], v[236:239], v[34:49]
	ds_read_b64_tr_b16 v[236:237], v191 offset:9728
	ds_read_b64_tr_b16 v[238:239], v191 offset:11776
	v_exp_f32_e32 v103, v103
	s_waitcnt lgkmcnt(10)
	v_mfma_f32_32x32x16_bf16 v[34:49], v[86:89], v[240:243], v[34:49]
	ds_read_b64_tr_b16 v[240:241], v191 offset:13824
	ds_read_b64_tr_b16 v[242:243], v191 offset:15872
	v_exp_f32_e32 v104, v104
	s_waitcnt lgkmcnt(10)
	v_mfma_f32_32x32x16_bf16 v[34:49], v[66:69], v[246:249], v[34:49]
	v_exp_f32_e32 v105, v105
	s_waitcnt lgkmcnt(8)
	v_mfma_f32_32x32x16_bf16 v[34:49], v[70:73], v[250:253], v[34:49]
	v_exp_f32_e32 v106, v106
	s_waitcnt lgkmcnt(6)
	v_mfma_f32_32x32x16_bf16 v[50:65], v[82:85], v[228:231], v[50:65]
	v_exp_f32_e32 v107, v107
	v_exp_f32_e32 v108, v108
	s_waitcnt lgkmcnt(4)
	v_mfma_f32_32x32x16_bf16 v[50:65], v[86:89], v[232:235], v[50:65]
	v_exp_f32_e32 v109, v109
	v_exp_f32_e32 v110, v110
	s_waitcnt lgkmcnt(2)
	v_mfma_f32_32x32x16_bf16 v[50:65], v[66:69], v[236:239], v[50:65]
	v_exp_f32_e32 v111, v111
	v_exp_f32_e32 v112, v112
	s_waitcnt lgkmcnt(0)
	v_mfma_f32_32x32x16_bf16 v[50:65], v[70:73], v[240:243], v[50:65]
	v_exp_f32_e32 v113, v113
	s_waitcnt vmcnt(5)
	s_barrier
; __device__ __forceinline__ void finishSM_fix(f32x16& p0, f32x16& p1, float& l_lane, bf16x8& pa0, bf16x8& pa1, bf16x8& pa2, bf16x8& pa3) {
; #pragma unroll
;   for (int r = 0; r < 16; ++r) p1[r] = __builtin_amdgcn_exp2f(p1[r]);
;   float ps = 0;
; #pragma unroll
;   for (int r = 0; r < 16; ++r) ps += p0[r];
; #pragma unroll
;   for (int r = 0; r < 16; ++r) ps += p1[r];
;   l_lane += ps;
;     ...
;   PK4(p0, 0, pa0); PK4(p0, 8, pa1); PK4(p1, 0, pa2); PK4(p1, 8, pa3);
;     ...
; }
; __device__ __forceinline__ void qkt12(f32x16& p0, f32x16& p1, const char* Ks, const bf16x8 (&qr)[12], const int (&kb)[4]) {
;   p0 = f32x16{}; p1 = f32x16{};
;     ...
;   bf16x8 c0 = KLD(0, 0), c1 = KLD(0, 1);
; #pragma unroll
;   for (int d0 = 0; d0 < 12; ++d0) {
;     bf16x8 n0 = c0, n1 = c1;
;     if (d0 < 11) { n0 = KLD(d0 + 1, 0); n1 = KLD(d0 + 1, 1); }
;     __builtin_amdgcn_sched_group_barrier(0x100, 2, 0);
;     p0 = __builtin_amdgcn_mfma_f32_32x32x16_bf16(c0, qr[d0], p0, 0, 0, 0);
;     p1 = __builtin_amdgcn_mfma_f32_32x32x16_bf16(c1, qr[d0], p1, 0, 0, 0);
;     __builtin_amdgcn_sched_group_barrier(0x008, 2, 0);
;     c0 = n0; c1 = n1; }
;     ...
; }
	s_mul_i32 s6, s25, 0x6000
	s_mul_i32 s10, s24, 0x6000
	s_lshl_b32 s11, s26, 14
	s_add_i32 s10, s43, s10
	s_add_i32 s11, s52, s11
	v_add_u32_e32 v187, s6, v183
	v_add_u32_e32 v188, s6, v184
	v_add_u32_e32 v189, s6, v185
	v_add_u32_e32 v190, s6, v186
	v_lshl_add_u32 v191, s24, 14, v182
	ds_read_b128 v[172:175], v187
	ds_read_b128 v[176:179], v187 offset:12288
	ds_read_b128 v[200:203], v188
	ds_read_b128 v[204:207], v188 offset:12288
	ds_read_b128 v[208:211], v189
	ds_read_b128 v[194:197], v189 offset:12288
	v_add_f32_e32 v198, v98, v99
	v_cvt_pk_bf16_f32 v98, v98, v99
	v_add_f32_e32 v199, v100, v101
	v_exp_f32_e32 v212, v212
	v_exp_f32_e32 v213, v213
	v_cvt_pk_bf16_f32 v99, v100, v101
	v_add_f32_e32 v198, v102, v198
	v_add_f32_e32 v199, v103, v199
	s_waitcnt lgkmcnt(5)
	v_mfma_f32_32x32x16_bf16 v[82:97], v[172:175], v[116:119], 0
	v_exp_f32_e32 v214, v214
	v_exp_f32_e32 v215, v215
	s_waitcnt lgkmcnt(4)
	v_mfma_f32_32x32x16_bf16 v[66:81], v[176:179], v[116:119], 0
	ds_read_b128 v[172:175], v190
	ds_read_b128 v[176:179], v190 offset:12288
	v_cvt_pk_bf16_f32 v100, v102, v103
	v_add_f32_e32 v198, v104, v198
	v_add_f32_e32 v199, v105, v199
	v_exp_f32_e32 v216, v216
	s_waitcnt lgkmcnt(5)
	v_mfma_f32_32x32x16_bf16 v[82:97], v[200:203], v[120:123], v[82:97]
	s_mov_b32 m0, s10
	v_lshl_add_u64 v[192:193], v[166:167], 0, s[94:95]
	global_load_lds_dwordx4 v[192:193], off
	v_exp_f32_e32 v217, v217
	s_waitcnt lgkmcnt(4)
	v_mfma_f32_32x32x16_bf16 v[66:81], v[204:207], v[120:123], v[66:81]
	ds_read_b128 v[200:203], v187 offset:128
	ds_read_b128 v[204:207], v187 offset:12416
	v_cvt_pk_bf16_f32 v101, v104, v105
	v_add_f32_e32 v198, v106, v198
	v_add_f32_e32 v199, v107, v199
	v_exp_f32_e32 v218, v218
	s_waitcnt lgkmcnt(5)
	v_mfma_f32_32x32x16_bf16 v[82:97], v[208:211], v[124:127], v[82:97]
	v_exp_f32_e32 v219, v219
	s_waitcnt lgkmcnt(4)
	v_mfma_f32_32x32x16_bf16 v[66:81], v[194:197], v[124:127], v[66:81]
	ds_read_b128 v[208:211], v188 offset:128
	ds_read_b128 v[194:197], v188 offset:12416
	v_cvt_pk_bf16_f32 v102, v106, v107
	v_add_f32_e32 v198, v108, v198
	v_add_f32_e32 v199, v109, v199
	v_exp_f32_e32 v220, v220
	s_waitcnt lgkmcnt(5)
	v_mfma_f32_32x32x16_bf16 v[82:97], v[172:175], v[128:131], v[82:97]
	s_add_i32 m0, s10, 0x400
	v_lshl_add_u64 v[192:193], v[168:169], 0, s[94:95]
	global_load_lds_dwordx4 v[192:193], off
	v_exp_f32_e32 v221, v221
	v_cvt_pk_bf16_f32 v103, v108, v109
	s_waitcnt lgkmcnt(4)
	v_mfma_f32_32x32x16_bf16 v[66:81], v[176:179], v[128:131], v[66:81]
	ds_read_b128 v[172:175], v189 offset:128
	ds_read_b128 v[176:179], v189 offset:12416
	v_add_f32_e32 v198, v110, v198
	v_add_f32_e32 v199, v111, v199
	v_exp_f32_e32 v222, v222
	s_waitcnt lgkmcnt(5)
	v_mfma_f32_32x32x16_bf16 v[82:97], v[200:203], v[132:135], v[82:97]
	v_exp_f32_e32 v223, v223
	v_cvt_pk_bf16_f32 v104, v110, v111
	s_waitcnt lgkmcnt(4)
	v_mfma_f32_32x32x16_bf16 v[66:81], v[204:207], v[132:135], v[66:81]
	ds_read_b128 v[200:203], v190 offset:128
	ds_read_b128 v[204:207], v190 offset:12416
	v_add_f32_e32 v198, v112, v198
	v_add_f32_e32 v199, v113, v199
	v_exp_f32_e32 v224, v224
	s_waitcnt lgkmcnt(5)
	v_mfma_f32_32x32x16_bf16 v[82:97], v[208:211], v[136:139], v[82:97]
	s_add_i32 m0, s10, 0x800
	v_lshl_add_u64 v[192:193], v[170:171], 0, s[94:95]
	global_load_lds_dwordx4 v[192:193], off
	v_exp_f32_e32 v225, v225
	v_cvt_pk_bf16_f32 v105, v112, v113
	s_waitcnt lgkmcnt(4)
	v_mfma_f32_32x32x16_bf16 v[66:81], v[194:197], v[136:139], v[66:81]
	ds_read_b128 v[208:211], v187 offset:256
	ds_read_b128 v[194:197], v187 offset:12544
	v_exp_f32_e32 v226, v226
	v_exp_f32_e32 v227, v227
	s_waitcnt lgkmcnt(5)
	v_mfma_f32_32x32x16_bf16 v[82:97], v[172:175], v[140:143], v[82:97]
	v_add_f32_e32 v198, v212, v198
	v_add_f32_e32 v199, v213, v199
	v_cvt_pk_bf16_f32 v212, v212, v213
	s_waitcnt lgkmcnt(4)
	v_mfma_f32_32x32x16_bf16 v[66:81], v[176:179], v[140:143], v[66:81]
	ds_read_b128 v[172:175], v188 offset:256
	ds_read_b128 v[176:179], v188 offset:12544
	v_permlane32_swap_b32_e32 v98, v100
	v_permlane32_swap_b32_e32 v99, v101
	v_permlane32_swap_b32_e32 v102, v104
	v_permlane32_swap_b32_e32 v103, v105
	s_waitcnt lgkmcnt(5)
	v_mfma_f32_32x32x16_bf16 v[82:97], v[200:203], v[144:147], v[82:97]
	s_mov_b64 s[22:23], 0x61e8c100
	s_mov_b32 m0, s11
	v_lshl_add_u64 v[192:193], v[164:165], 0, s[22:23]
	global_load_lds_dwordx4 v[192:193], off
	v_add_f32_e32 v198, v214, v198
	v_add_f32_e32 v199, v215, v199
	v_cvt_pk_bf16_f32 v213, v214, v215
	s_waitcnt lgkmcnt(4)
	v_mfma_f32_32x32x16_bf16 v[66:81], v[204:207], v[144:147], v[66:81]
	ds_read_b128 v[200:203], v189 offset:256
	ds_read_b128 v[204:207], v189 offset:12544
	v_add_f32_e32 v198, v216, v198
	v_add_f32_e32 v199, v217, v199
	v_cvt_pk_bf16_f32 v214, v216, v217
	v_add_f32_e32 v198, v218, v198
	s_waitcnt lgkmcnt(5)
	v_mfma_f32_32x32x16_bf16 v[82:97], v[208:211], v[152:155], v[82:97]
	ds_read_b64_tr_b16 v[228:229], v191 offset:0
	ds_read_b64_tr_b16 v[230:231], v191 offset:2048
	v_add_f32_e32 v199, v219, v199
	v_cvt_pk_bf16_f32 v215, v218, v219
	v_add_f32_e32 v198, v220, v198
	v_add_f32_e32 v199, v221, v199
	s_waitcnt lgkmcnt(6)
	v_mfma_f32_32x32x16_bf16 v[66:81], v[194:197], v[152:155], v[66:81]
	ds_read_b128 v[208:211], v190 offset:256
	ds_read_b128 v[194:197], v190 offset:12544
	ds_read_b64_tr_b16 v[232:233], v191 offset:4096
	ds_read_b64_tr_b16 v[234:235], v191 offset:6144
	v_cvt_pk_bf16_f32 v216, v220, v221
	v_add_f32_e32 v198, v222, v198
	v_add_f32_e32 v199, v223, v199
	s_waitcnt lgkmcnt(9)
; #define SBAR() __builtin_amdgcn_sched_barrier(0)
; #define TOP(t, st) do { if ((t) + 2 < NT) asm volatile("s_waitcnt vmcnt(5)" ::: "memory"); else asm volatile("s_waitcnt vmcnt(0)" ::: "memory"); \
;     __builtin_amdgcn_s_barrier(); asm volatile("" ::: "memory"); \
;     if ((t) + 2 < NT) KDMA((t) + 2, NEXT3(NEXT3(st))); if ((t) + 1 < NT) VDMA((t) + 1, NEXT3(st)); } while (0)
; template <int D0> __device__ __forceinline__ void pv_one(f32x16& od, int vb, bf16x8 pa0, bf16x8 pa1, bf16x8 pa2, bf16x8 pa3) {
;   const s16x4 l0 = tr_read<v_rd_off(D0, 0, 0)>(vb), h0 = tr_read<v_rd_off(D0, 0, 1)>(vb), l1 = tr_read<v_rd_off(D0, 1, 0)>(vb), h1 = tr_read<v_rd_off(D0, 1, 1)>(vb);
;   const s16x4 l2 = tr_read<v_rd_off(D0, 2, 0)>(vb), h2 = tr_read<v_rd_off(D0, 2, 1)>(vb), l3 = tr_read<v_rd_off(D0, 3, 0)>(vb), h3 = tr_read<v_rd_off(D0, 3, 1)>(vb);
;   asm volatile("s_waitcnt lgkmcnt(0)" ::: "memory"); SBAR();
;     ...
;   od = __builtin_amdgcn_mfma_f32_32x32x16_bf16(pa0, PK(l0, h0), od, 0, 0, 0);
;   od = __builtin_amdgcn_mfma_f32_32x32x16_bf16(pa1, PK(l1, h1), od, 0, 0, 0);
;   od = __builtin_amdgcn_mfma_f32_32x32x16_bf16(pa2, PK(l2, h2), od, 0, 0, 0);
;   od = __builtin_amdgcn_mfma_f32_32x32x16_bf16(pa3, PK(l3, h3), od, 0, 0, 0);
;     ...
; }
; __device__ __forceinline__ void pv_d0(f32x16 (&o)[4], int vb, bf16x8 pa0, bf16x8 pa1, bf16x8 pa2, bf16x8 pa3) {
;   pv_one<0>(o[0], vb, pa0, pa1, pa2, pa3); pv_one<1>(o[1], vb, pa0, pa1, pa2, pa3); pv_one<2>(o[2], vb, pa0, pa1, pa2, pa3); pv_one<3>(o[3], vb, pa0, pa1, pa2, pa3);
; __device__ __forceinline__ void attn_unit_dma(const bf16_t* __restrict__ Qb, const bf16_t* __restrict__ Kh, const bf16_t* __restrict__ Vh, int seq, char* lds, LAS unsigned char* ldsl, ...
;     ...
;   for (int j = 1; j + 1 < NT; j += 2) {
;     int sp = st; st = NEXT3(st);
;     TOP(j, st);
;     SBAR(); qkt12(pB0, pB1, lds + DMA_KRING + st * SHM_K, qr, kb);
;     finishSM_fix(pA0, pA1, l_reg, pa0, pa1, pa2, pa3); SBAR();
;     pv_d0(o, vb0 + sp * SHM_V, pa0, pa1, pa2, pa3); partialSM_fix(pB0, pB1);
;     sp = st; st = NEXT3(st);
;     TOP(j + 1, st);
;     SBAR(); qkt12(pA0, pA1, lds + DMA_KRING + st * SHM_K, qr, kb);
;     finishSM_fix(pB0, pB1, l_reg, pa0, pa1, pa2, pa3); SBAR();
;     pv_d0(o, vb0 + sp * SHM_V, pa0, pa1, pa2, pa3); partialSM_fix(pA0, pA1);
;   }
	v_mfma_f32_32x32x16_bf16 v[82:97], v[172:175], v[148:151], v[82:97]
	ds_read_b64_tr_b16 v[236:237], v191 offset:8192
	ds_read_b64_tr_b16 v[238:239], v191 offset:10240
	s_mov_b64 s[22:23], 0x61e8c180
	s_add_i32 m0, s11, 0x400
	v_lshl_add_u64 v[192:193], v[164:165], 0, s[22:23]
	global_load_lds_dwordx4 v[192:193], off
	v_cvt_pk_bf16_f32 v217, v222, v223
	v_add_f32_e32 v198, v224, v198
	v_add_f32_e32 v199, v225, v199
	v_cvt_pk_bf16_f32 v218, v224, v225
	s_waitcnt lgkmcnt(10)
	v_mfma_f32_32x32x16_bf16 v[66:81], v[176:179], v[148:151], v[66:81]
	ds_read_b64_tr_b16 v[240:241], v191 offset:12288
	ds_read_b64_tr_b16 v[242:243], v191 offset:14336
	v_add_f32_e32 v198, v226, v198
	v_add_f32_e32 v199, v227, v199
	v_cvt_pk_bf16_f32 v219, v226, v227
	s_waitcnt lgkmcnt(11)
	v_mfma_f32_32x32x16_bf16 v[82:97], v[200:203], v[160:163], v[82:97]
	ds_read_b64_tr_b16 v[246:247], v191 offset:512
	ds_read_b64_tr_b16 v[248:249], v191 offset:2560
	v_add_f32_e32 v198, v198, v199
	s_nop 0
	v_permlane32_swap_b32_e32 v212, v214
	v_permlane32_swap_b32_e32 v213, v215
	s_waitcnt lgkmcnt(12)
	v_mfma_f32_32x32x16_bf16 v[66:81], v[204:207], v[160:163], v[66:81]
	ds_read_b64_tr_b16 v[250:251], v191 offset:4608
	ds_read_b64_tr_b16 v[252:253], v191 offset:6656
	v_permlane32_swap_b32_e32 v216, v218
	v_permlane32_swap_b32_e32 v217, v219
	v_add_f32_e32 v114, v114, v198
	s_waitcnt lgkmcnt(11)
	v_mfma_f32_32x32x16_bf16 v[82:97], v[208:211], v[156:159], v[82:97]
	s_waitcnt lgkmcnt(10)
	v_mfma_f32_32x32x16_bf16 v[66:81], v[194:197], v[156:159], v[66:81]
	v_mfma_f32_32x32x16_bf16 v[2:17], v[98:101], v[228:231], v[2:17]
	ds_read_b64_tr_b16 v[228:229], v191 offset:8704
	ds_read_b64_tr_b16 v[230:231], v191 offset:10752
	s_waitcnt lgkmcnt(10)
	v_mfma_f32_32x32x16_bf16 v[2:17], v[102:105], v[232:235], v[2:17]
	ds_read_b64_tr_b16 v[232:233], v191 offset:12800
	ds_read_b64_tr_b16 v[234:235], v191 offset:14848
	s_waitcnt lgkmcnt(10)
	v_mfma_f32_32x32x16_bf16 v[2:17], v[212:215], v[236:239], v[2:17]
	ds_read_b64_tr_b16 v[236:237], v191 offset:1024
	ds_read_b64_tr_b16 v[238:239], v191 offset:3072
	v_lshl_add_u64 v[166:167], v[166:167], 0, s[90:91]
	s_waitcnt lgkmcnt(10)
	v_mfma_f32_32x32x16_bf16 v[2:17], v[216:219], v[240:243], v[2:17]
	ds_read_b64_tr_b16 v[240:241], v191 offset:5120
	ds_read_b64_tr_b16 v[242:243], v191 offset:7168
	v_exp_f32_e32 v82, v82
	v_lshl_add_u64 v[168:169], v[168:169], 0, s[90:91]
	s_waitcnt lgkmcnt(10)
	v_mfma_f32_32x32x16_bf16 v[18:33], v[98:101], v[246:249], v[18:33]
	ds_read_b64_tr_b16 v[246:247], v191 offset:9216
	ds_read_b64_tr_b16 v[248:249], v191 offset:11264
	v_exp_f32_e32 v83, v83
	v_lshl_add_u64 v[170:171], v[170:171], 0, s[90:91]
	s_waitcnt lgkmcnt(10)
	v_mfma_f32_32x32x16_bf16 v[18:33], v[102:105], v[250:253], v[18:33]
	ds_read_b64_tr_b16 v[250:251], v191 offset:13312
	ds_read_b64_tr_b16 v[252:253], v191 offset:15360
	v_exp_f32_e32 v84, v84
	v_lshl_add_u64 v[164:165], v[164:165], 0, s[68:69]
	s_waitcnt lgkmcnt(10)
	v_mfma_f32_32x32x16_bf16 v[18:33], v[212:215], v[228:231], v[18:33]
	ds_read_b64_tr_b16 v[228:229], v191 offset:1536
	ds_read_b64_tr_b16 v[230:231], v191 offset:3584
	v_exp_f32_e32 v85, v85
	s_waitcnt lgkmcnt(10)
	v_mfma_f32_32x32x16_bf16 v[18:33], v[216:219], v[232:235], v[18:33]
	ds_read_b64_tr_b16 v[232:233], v191 offset:5632
	ds_read_b64_tr_b16 v[234:235], v191 offset:7680
	v_exp_f32_e32 v86, v86
	s_waitcnt lgkmcnt(10)
	v_mfma_f32_32x32x16_bf16 v[34:49], v[98:101], v[236:239], v[34:49]
	ds_read_b64_tr_b16 v[236:237], v191 offset:9728
	ds_read_b64_tr_b16 v[238:239], v191 offset:11776
	v_exp_f32_e32 v87, v87
	s_waitcnt lgkmcnt(10)
	v_mfma_f32_32x32x16_bf16 v[34:49], v[102:105], v[240:243], v[34:49]
	ds_read_b64_tr_b16 v[240:241], v191 offset:13824
	ds_read_b64_tr_b16 v[242:243], v191 offset:15872
	v_exp_f32_e32 v88, v88
	s_waitcnt lgkmcnt(10)
	v_mfma_f32_32x32x16_bf16 v[34:49], v[212:215], v[246:249], v[34:49]
	v_exp_f32_e32 v89, v89
	s_waitcnt lgkmcnt(8)
	v_mfma_f32_32x32x16_bf16 v[34:49], v[216:219], v[250:253], v[34:49]
	v_exp_f32_e32 v90, v90
	s_waitcnt lgkmcnt(6)
	v_mfma_f32_32x32x16_bf16 v[50:65], v[98:101], v[228:231], v[50:65]
	v_exp_f32_e32 v91, v91
	v_exp_f32_e32 v92, v92
	s_waitcnt lgkmcnt(4)
	v_mfma_f32_32x32x16_bf16 v[50:65], v[102:105], v[232:235], v[50:65]
	v_exp_f32_e32 v93, v93
	v_exp_f32_e32 v94, v94
	s_waitcnt lgkmcnt(2)
	v_mfma_f32_32x32x16_bf16 v[50:65], v[212:215], v[236:239], v[50:65]
	v_exp_f32_e32 v95, v95
	v_exp_f32_e32 v96, v96
	s_waitcnt lgkmcnt(0)
	v_mfma_f32_32x32x16_bf16 v[50:65], v[216:219], v[240:243], v[50:65]
	v_exp_f32_e32 v97, v97
	s_mov_b32 s26, s25
	s_add_i32 s72, s72, 2
	s_cmp_lt_u32 s72, s37
	s_cbranch_scc1 .Lfa_loop
	v_mov_b32_e32 v195, v82
	v_mov_b32_e32 v216, v83
	v_mov_b32_e32 v213, v84
	v_mov_b32_e32 v215, v85
	v_mov_b32_e32 v197, v86
	v_mov_b32_e32 v214, v87
	v_mov_b32_e32 v196, v88
	v_mov_b32_e32 v212, v89
	v_mov_b32_e32 v191, v90
	v_mov_b32_e32 v193, v91
	v_mov_b32_e32 v189, v92
	v_mov_b32_e32 v192, v93
	v_mov_b32_e32 v188, v94
	v_mov_b32_e32 v190, v95
	v_mov_b32_e32 v187, v96
	v_mov_b32_e32 v194, v97
	s_branch .LBB0_853
	s_nop 0
	s_nop 0
	s_nop 0
	s_nop 0
	s_nop 0
	s_nop 0
	s_nop 0
	s_nop 0
; #define SBAR() __builtin_amdgcn_sched_barrier(0)
; #define TOP(t, st) do { if ((t) + 2 < NT) asm volatile("s_waitcnt vmcnt(5)" ::: "memory"); else asm volatile("s_waitcnt vmcnt(0)" ::: "memory"); \
;     __builtin_amdgcn_s_barrier(); asm volatile("" ::: "memory"); \
;     if ((t) + 2 < NT) KDMA((t) + 2, NEXT3(NEXT3(st))); if ((t) + 1 < NT) VDMA((t) + 1, NEXT3(st)); } while (0)
; __device__ __forceinline__ void attn_unit_dma(const bf16_t* __restrict__ Qb, const bf16_t* __restrict__ Kh, const bf16_t* __restrict__ Vh, int seq, char* lds, LAS unsigned char* ldsl, ...
;     ...
;   { int sp = st; st = NEXT3(st);
;     TOP(NT - 1, st);
;     SBAR(); qkt12(pB0, pB1, lds + DMA_KRING + st * SHM_K, qr, kb);
;     finishSM_fix(pA0, pA1, l_reg, pa0, pa1, pa2, pa3); SBAR();
;     pv_d0(o, vb0 + sp * SHM_V, pa0, pa1, pa2, pa3); partialSM_fix(pB0, pB1);
;     finishSM_fix(pB0, pB1, l_reg, pa0, pa1, pa2, pa3); SBAR();
;     pv_d0(o, vb0 + st * SHM_V, pa0, pa1, pa2, pa3); }
.LBB0_869:
	v_mov_b32_e32 v199, 1
	v_mov_b32_e32 v198, 0x358637bd
	v_mov_b64_e32 v[210:211], 0x3ff
	v_mov_b64_e32 v[208:209], 0x400
	v_mov_b64_e32 v[200:201], 0x420
	v_mov_b64_e32 v[202:203], 0x41f
	v_mov_b64_e32 v[204:205], 0x100
	v_mov_b64_e32 v[206:207], 0xff
	s_and_b32 s6, s63, 0x3fffffc0
	s_lshl_b32 s6, s6, 2
	s_add_i32 s10, s6, 0
	s_add_i32 s10, s10, 0x1e000
	s_add_i32 s6, s26, 1
	s_waitcnt vmcnt(0)
	s_barrier
	s_cmp_lg_u32 s26, 2
	s_cselect_b32 s6, s6, 0
	s_mul_i32 s7, s6, 0x6000
	s_add_i32 s7, s7, 0
	v_add_u32_e32 v168, s7, v183
	ds_read_b128 v[82:85], v168
	ds_read_b128 v[86:89], v168 offset:12288
	v_add_u32_e32 v169, s7, v184
	v_add_u32_e32 v170, s7, v185
	v_exp_f32_e32 v81, v81
	s_waitcnt lgkmcnt(0)
	v_mfma_f32_32x32x16_bf16 v[98:113], v[82:85], v[116:119], 0
	v_mfma_f32_32x32x16_bf16 v[82:97], v[86:89], v[116:119], 0
	ds_read_b128 v[116:119], v169
	ds_read_b128 v[164:167], v169 offset:12288
	s_waitcnt lgkmcnt(0)
	v_mfma_f32_32x32x16_bf16 v[98:113], v[116:119], v[120:123], v[98:113]
	v_mfma_f32_32x32x16_bf16 v[82:97], v[164:167], v[120:123], v[82:97]
	ds_read_b128 v[116:119], v170
	ds_read_b128 v[120:123], v170 offset:12288
	v_add_u32_e32 v164, s7, v186
	s_waitcnt lgkmcnt(0)
	v_mfma_f32_32x32x16_bf16 v[98:113], v[116:119], v[124:127], v[98:113]
	v_mfma_f32_32x32x16_bf16 v[82:97], v[120:123], v[124:127], v[82:97]
	ds_read_b128 v[116:119], v164
	ds_read_b128 v[120:123], v164 offset:12288
	v_exp_f32_e32 v124, v74
	v_exp_f32_e32 v125, v75
	v_exp_f32_e32 v126, v76
	v_exp_f32_e32 v127, v77
	s_waitcnt lgkmcnt(0)
	v_mfma_f32_32x32x16_bf16 v[98:113], v[116:119], v[128:131], v[98:113]
	v_mfma_f32_32x32x16_bf16 v[82:97], v[120:123], v[128:131], v[82:97]
	ds_read_b128 v[116:119], v168 offset:128
	ds_read_b128 v[120:123], v168 offset:12416
	v_exp_f32_e32 v128, v78
	v_exp_f32_e32 v129, v79
	v_exp_f32_e32 v130, v80
	s_waitcnt lgkmcnt(0)
	v_mfma_f32_32x32x16_bf16 v[98:113], v[116:119], v[132:135], v[98:113]
	v_mfma_f32_32x32x16_bf16 v[82:97], v[120:123], v[132:135], v[82:97]
	ds_read_b128 v[116:119], v169 offset:128
	ds_read_b128 v[120:123], v169 offset:12416
	s_waitcnt lgkmcnt(0)
	v_mfma_f32_32x32x16_bf16 v[98:113], v[116:119], v[136:139], v[98:113]
	v_mfma_f32_32x32x16_bf16 v[82:97], v[120:123], v[136:139], v[82:97]
	ds_read_b128 v[116:119], v170 offset:128
	ds_read_b128 v[120:123], v170 offset:12416
	s_waitcnt lgkmcnt(0)
	v_mfma_f32_32x32x16_bf16 v[98:113], v[116:119], v[140:143], v[98:113]
	v_mfma_f32_32x32x16_bf16 v[82:97], v[120:123], v[140:143], v[82:97]
	ds_read_b128 v[116:119], v164 offset:128
	ds_read_b128 v[120:123], v164 offset:12416
	s_waitcnt lgkmcnt(0)
	v_mfma_f32_32x32x16_bf16 v[98:113], v[116:119], v[144:147], v[98:113]
	v_mfma_f32_32x32x16_bf16 v[82:97], v[120:123], v[144:147], v[82:97]
	ds_read_b128 v[116:119], v168 offset:256
	ds_read_b128 v[120:123], v168 offset:12544
	s_waitcnt lgkmcnt(0)
	v_mfma_f32_32x32x16_bf16 v[98:113], v[116:119], v[152:155], v[98:113]
	v_mfma_f32_32x32x16_bf16 v[82:97], v[120:123], v[152:155], v[82:97]
	ds_read_b128 v[116:119], v169 offset:256
	ds_read_b128 v[120:123], v169 offset:12544
	s_waitcnt lgkmcnt(0)
	v_mfma_f32_32x32x16_bf16 v[98:113], v[116:119], v[148:151], v[98:113]
	v_mfma_f32_32x32x16_bf16 v[82:97], v[120:123], v[148:151], v[82:97]
	ds_read_b128 v[116:119], v170 offset:256
	ds_read_b128 v[120:123], v170 offset:12544
	s_waitcnt lgkmcnt(0)
	v_mfma_f32_32x32x16_bf16 v[98:113], v[116:119], v[160:163], v[98:113]
	v_mfma_f32_32x32x16_bf16 v[82:97], v[120:123], v[160:163], v[82:97]
	ds_read_b128 v[116:119], v164 offset:256
	ds_read_b128 v[120:123], v164 offset:12544
	s_waitcnt lgkmcnt(0)
	v_mfma_f32_32x32x16_bf16 v[98:113], v[116:119], v[156:159], v[98:113]
	v_exp_f32_e32 v116, v66
	v_add_f32_e32 v66, 0, v195
	v_add_f32_e32 v66, v216, v66
	v_add_f32_e32 v66, v213, v66
	v_add_f32_e32 v66, v215, v66
	v_add_f32_e32 v66, v197, v66
	v_add_f32_e32 v66, v214, v66
	v_add_f32_e32 v66, v196, v66
	v_add_f32_e32 v66, v212, v66
	v_add_f32_e32 v66, v191, v66
	v_add_f32_e32 v66, v193, v66
	v_add_f32_e32 v66, v189, v66
	v_add_f32_e32 v66, v192, v66
	v_add_f32_e32 v66, v188, v66
	v_exp_f32_e32 v117, v67
	v_add_f32_e32 v66, v190, v66
	v_exp_f32_e32 v118, v68
	v_add_f32_e32 v66, v187, v66
	v_exp_f32_e32 v119, v69
	v_add_f32_e32 v66, v194, v66
	v_mfma_f32_32x32x16_bf16 v[82:97], v[120:123], v[156:159], v[82:97]
	v_exp_f32_e32 v120, v70
	v_add_f32_e32 v66, v116, v66
	v_exp_f32_e32 v121, v71
	v_add_f32_e32 v66, v117, v66
	v_exp_f32_e32 v122, v72
	v_add_f32_e32 v66, v118, v66
	v_exp_f32_e32 v123, v73
	v_add_f32_e32 v66, v119, v66
	v_add_f32_e32 v66, v120, v66
	v_add_f32_e32 v66, v121, v66
	v_add_f32_e32 v66, v122, v66
	v_add_f32_e32 v66, v123, v66
	v_add_f32_e32 v66, v124, v66
	v_add_f32_e32 v66, v125, v66
	v_add_f32_e32 v66, v126, v66
	v_add_f32_e32 v66, v127, v66
	v_add_f32_e32 v66, v128, v66
	v_add_f32_e32 v66, v129, v66
	v_add_f32_e32 v66, v130, v66
	v_add_f32_e32 v66, v81, v66
	v_add_f32_e32 v114, v114, v66
	v_cvt_pk_bf16_f32 v66, v195, v216
	v_cvt_pk_bf16_f32 v67, v213, v215
	v_cvt_pk_bf16_f32 v68, v197, v214
	v_cvt_pk_bf16_f32 v69, v196, v212
	v_cvt_pk_bf16_f32 v70, v191, v193
	v_cvt_pk_bf16_f32 v71, v189, v192
	v_cvt_pk_bf16_f32 v72, v188, v190
	v_cvt_pk_bf16_f32 v73, v187, v194
	s_nop 0
	v_permlane32_swap_b32_e32 v66, v68
	v_permlane32_swap_b32_e32 v67, v69
	v_cvt_pk_bf16_f32 v74, v116, v117
	v_cvt_pk_bf16_f32 v75, v118, v119
	v_cvt_pk_bf16_f32 v76, v120, v121
	v_cvt_pk_bf16_f32 v77, v122, v123
	v_cvt_pk_bf16_f32 v78, v124, v125
	v_cvt_pk_bf16_f32 v79, v126, v127
	v_cvt_pk_bf16_f32 v80, v128, v129
	v_cvt_pk_bf16_f32 v81, v130, v81
	v_permlane32_swap_b32_e32 v70, v72
	v_permlane32_swap_b32_e32 v71, v73
	v_permlane32_swap_b32_e32 v74, v76
	v_permlane32_swap_b32_e32 v75, v77
	v_permlane32_swap_b32_e32 v78, v80
	v_permlane32_swap_b32_e32 v79, v81
	v_lshl_add_u32 v132, s26, 14, v182
	ds_read_b64_tr_b16 v[116:117], v132 offset:0
	ds_read_b64_tr_b16 v[118:119], v132 offset:0x800
	ds_read_b64_tr_b16 v[120:121], v132 offset:0x1000
	ds_read_b64_tr_b16 v[122:123], v132 offset:0x1800
	ds_read_b64_tr_b16 v[124:125], v132 offset:0x2000
	ds_read_b64_tr_b16 v[126:127], v132 offset:0x2800
	ds_read_b64_tr_b16 v[128:129], v132 offset:0x3000
	ds_read_b64_tr_b16 v[130:131], v132 offset:0x3800
	s_waitcnt lgkmcnt(0)
; #define SBAR() __builtin_amdgcn_sched_barrier(0)
; __device__ __forceinline__ void attn_unit_dma(const bf16_t* __restrict__ Qb, const bf16_t* __restrict__ Kh, const bf16_t* __restrict__ Vh, int seq, char* lds, LAS unsigned char* ldsl, ...
;     ...
;     finishSM_fix(pA0, pA1, l_reg, pa0, pa1, pa2, pa3); SBAR();
;     pv_d0(o, vb0 + sp * SHM_V, pa0, pa1, pa2, pa3); partialSM_fix(pB0, pB1);
;     finishSM_fix(pB0, pB1, l_reg, pa0, pa1, pa2, pa3); SBAR();
;     pv_d0(o, vb0 + st * SHM_V, pa0, pa1, pa2, pa3); }
	s_nop 0
	v_mfma_f32_32x32x16_bf16 v[2:17], v[66:69], v[116:119], v[2:17]
	ds_read_b64_tr_b16 v[116:117], v132 offset:0x200
	ds_read_b64_tr_b16 v[118:119], v132 offset:0xa00
	v_mfma_f32_32x32x16_bf16 v[2:17], v[70:73], v[120:123], v[2:17]
	ds_read_b64_tr_b16 v[120:121], v132 offset:0x1200
	ds_read_b64_tr_b16 v[122:123], v132 offset:0x1a00
	v_mfma_f32_32x32x16_bf16 v[2:17], v[74:77], v[124:127], v[2:17]
	ds_read_b64_tr_b16 v[124:125], v132 offset:0x2200
	ds_read_b64_tr_b16 v[126:127], v132 offset:0x2a00
	v_mfma_f32_32x32x16_bf16 v[2:17], v[78:81], v[128:131], v[2:17]
	ds_read_b64_tr_b16 v[128:129], v132 offset:0x3200
	ds_read_b64_tr_b16 v[130:131], v132 offset:0x3a00
	s_waitcnt lgkmcnt(0)
	v_mfma_f32_32x32x16_bf16 v[18:33], v[66:69], v[116:119], v[18:33]
	ds_read_b64_tr_b16 v[116:117], v132 offset:0x400
	ds_read_b64_tr_b16 v[118:119], v132 offset:0xc00
	v_mfma_f32_32x32x16_bf16 v[18:33], v[70:73], v[120:123], v[18:33]
	ds_read_b64_tr_b16 v[120:121], v132 offset:0x1400
	ds_read_b64_tr_b16 v[122:123], v132 offset:0x1c00
	v_mfma_f32_32x32x16_bf16 v[18:33], v[74:77], v[124:127], v[18:33]
	ds_read_b64_tr_b16 v[124:125], v132 offset:0x2400
	ds_read_b64_tr_b16 v[126:127], v132 offset:0x2c00
	v_mfma_f32_32x32x16_bf16 v[18:33], v[78:81], v[128:131], v[18:33]
	ds_read_b64_tr_b16 v[128:129], v132 offset:0x3400
	ds_read_b64_tr_b16 v[130:131], v132 offset:0x3c00
	s_waitcnt lgkmcnt(0)
	v_mfma_f32_32x32x16_bf16 v[34:49], v[66:69], v[116:119], v[34:49]
	ds_read_b64_tr_b16 v[116:117], v132 offset:0x600
	ds_read_b64_tr_b16 v[118:119], v132 offset:0xe00
	v_mfma_f32_32x32x16_bf16 v[34:49], v[70:73], v[120:123], v[34:49]
	ds_read_b64_tr_b16 v[120:121], v132 offset:0x1600
	ds_read_b64_tr_b16 v[122:123], v132 offset:0x1e00
	v_mfma_f32_32x32x16_bf16 v[34:49], v[74:77], v[124:127], v[34:49]
	ds_read_b64_tr_b16 v[124:125], v132 offset:0x2600
	ds_read_b64_tr_b16 v[126:127], v132 offset:0x2e00
	v_mfma_f32_32x32x16_bf16 v[34:49], v[78:81], v[128:131], v[34:49]
	ds_read_b64_tr_b16 v[128:129], v132 offset:0x3600
	ds_read_b64_tr_b16 v[130:131], v132 offset:0x3e00
	s_waitcnt lgkmcnt(0)
	v_mfma_f32_32x32x16_bf16 v[50:65], v[66:69], v[116:119], v[50:65]
	v_exp_f32_e32 v67, v98
	v_exp_f32_e32 v68, v99
	v_exp_f32_e32 v69, v100
	v_exp_f32_e32 v98, v113
	v_add_f32_e32 v66, 0, v67
	v_add_f32_e32 v66, v68, v66
	v_add_f32_e32 v66, v69, v66
	v_mfma_f32_32x32x16_bf16 v[50:65], v[70:73], v[120:123], v[50:65]
	v_exp_f32_e32 v70, v101
	v_exp_f32_e32 v71, v102
	v_exp_f32_e32 v72, v103
	v_exp_f32_e32 v73, v104
	v_add_f32_e32 v66, v70, v66
	v_add_f32_e32 v66, v71, v66
	v_add_f32_e32 v66, v72, v66
	v_mfma_f32_32x32x16_bf16 v[50:65], v[74:77], v[124:127], v[50:65]
	v_exp_f32_e32 v74, v105
	v_exp_f32_e32 v75, v106
	v_exp_f32_e32 v76, v107
	v_exp_f32_e32 v77, v108
	v_add_f32_e32 v66, v73, v66
	v_add_f32_e32 v66, v74, v66
	v_add_f32_e32 v66, v75, v66
	v_mfma_f32_32x32x16_bf16 v[50:65], v[78:81], v[128:131], v[50:65]
	v_exp_f32_e32 v78, v109
	v_exp_f32_e32 v79, v110
	v_exp_f32_e32 v80, v111
	v_add_f32_e32 v66, v76, v66
	v_exp_f32_e32 v81, v112
	v_add_f32_e32 v66, v77, v66
	v_add_f32_e32 v66, v78, v66
	v_exp_f32_e32 v82, v82
	v_add_f32_e32 v66, v79, v66
	v_exp_f32_e32 v83, v83
	v_add_f32_e32 v66, v80, v66
	v_exp_f32_e32 v84, v84
	v_add_f32_e32 v66, v81, v66
	v_exp_f32_e32 v85, v85
	v_add_f32_e32 v66, v98, v66
	v_exp_f32_e32 v86, v86
	v_add_f32_e32 v66, v82, v66
	v_exp_f32_e32 v87, v87
	v_add_f32_e32 v66, v83, v66
	v_exp_f32_e32 v88, v88
	v_add_f32_e32 v66, v84, v66
	v_exp_f32_e32 v89, v89
	v_add_f32_e32 v66, v85, v66
	v_exp_f32_e32 v90, v90
	v_add_f32_e32 v66, v86, v66
	v_exp_f32_e32 v91, v91
	v_add_f32_e32 v66, v87, v66
	v_exp_f32_e32 v92, v92
	v_add_f32_e32 v66, v88, v66
	v_exp_f32_e32 v93, v93
	v_add_f32_e32 v66, v89, v66
	v_exp_f32_e32 v94, v94
	v_add_f32_e32 v66, v90, v66
	v_exp_f32_e32 v95, v95
	v_add_f32_e32 v66, v91, v66
	v_exp_f32_e32 v96, v96
	v_add_f32_e32 v66, v92, v66
	v_exp_f32_e32 v97, v97
	v_add_f32_e32 v66, v93, v66
	v_add_f32_e32 v66, v94, v66
	v_add_f32_e32 v66, v95, v66
	v_add_f32_e32 v66, v96, v66
	v_add_f32_e32 v66, v97, v66
	v_add_f32_e32 v66, v114, v66
	v_cvt_pk_bf16_f32 v68, v67, v68
	v_cvt_pk_bf16_f32 v69, v69, v70
	v_cvt_pk_bf16_f32 v70, v71, v72
	v_cvt_pk_bf16_f32 v71, v73, v74
	v_cvt_pk_bf16_f32 v72, v75, v76
	v_cvt_pk_bf16_f32 v73, v77, v78
	v_cvt_pk_bf16_f32 v74, v79, v80
	v_cvt_pk_bf16_f32 v75, v81, v98
	v_cvt_pk_bf16_f32 v76, v82, v83
	v_cvt_pk_bf16_f32 v77, v84, v85
	v_cvt_pk_bf16_f32 v78, v86, v87
	v_cvt_pk_bf16_f32 v79, v88, v89
	v_cvt_pk_bf16_f32 v80, v90, v91
	v_cvt_pk_bf16_f32 v81, v92, v93
	v_cvt_pk_bf16_f32 v82, v94, v95
	v_cvt_pk_bf16_f32 v83, v96, v97
	s_nop 0
	v_permlane32_swap_b32_e32 v68, v70
	v_permlane32_swap_b32_e32 v69, v71
	v_permlane32_swap_b32_e32 v72, v74
	v_permlane32_swap_b32_e32 v73, v75
	v_permlane32_swap_b32_e32 v76, v78
	v_permlane32_swap_b32_e32 v77, v79
	v_permlane32_swap_b32_e32 v80, v82
	v_permlane32_swap_b32_e32 v81, v83
	v_lshl_add_u32 v67, s6, 14, v182
	ds_read_b64_tr_b16 v[84:85], v67 offset:0
	ds_read_b64_tr_b16 v[86:87], v67 offset:0x800
	ds_read_b64_tr_b16 v[88:89], v67 offset:0x1000
	ds_read_b64_tr_b16 v[90:91], v67 offset:0x1800
	ds_read_b64_tr_b16 v[92:93], v67 offset:0x2000
	ds_read_b64_tr_b16 v[94:95], v67 offset:0x2800
	ds_read_b64_tr_b16 v[96:97], v67 offset:0x3000
	ds_read_b64_tr_b16 v[98:99], v67 offset:0x3800
	s_waitcnt lgkmcnt(0)
; __device__ __forceinline__ void attn_unit_dma(const bf16_t* __restrict__ Qb, const bf16_t* __restrict__ Kh, const bf16_t* __restrict__ Vh, int seq, char* lds, LAS unsigned char* ldsl, ...
;     ...
;     pv_d0(o, vb0 + st * SHM_V, pa0, pa1, pa2, pa3); }
;   { auto rr_ = __builtin_amdgcn_permlane32_swap(__float_as_uint(l_reg), __float_as_uint(l_reg), false, false); l_reg = __uint_as_float(rr_[0]) + __uint_as_float(rr_[1]); }
;   if (hi == 0) li_l[r32] = l_reg; asm volatile("s_waitcnt vmcnt(0) lgkmcnt(0)" ::: "memory");
;   __syncthreads();
	s_nop 0
	v_mfma_f32_32x32x16_bf16 v[2:17], v[68:71], v[84:87], v[2:17]
	ds_read_b64_tr_b16 v[84:85], v67 offset:0x200
	ds_read_b64_tr_b16 v[86:87], v67 offset:0xa00
	v_mfma_f32_32x32x16_bf16 v[2:17], v[72:75], v[88:91], v[2:17]
	ds_read_b64_tr_b16 v[88:89], v67 offset:0x1200
	ds_read_b64_tr_b16 v[90:91], v67 offset:0x1a00
	v_mfma_f32_32x32x16_bf16 v[2:17], v[76:79], v[92:95], v[2:17]
	ds_read_b64_tr_b16 v[92:93], v67 offset:0x2200
	ds_read_b64_tr_b16 v[94:95], v67 offset:0x2a00
	v_mfma_f32_32x32x16_bf16 v[2:17], v[80:83], v[96:99], v[2:17]
	ds_read_b64_tr_b16 v[96:97], v67 offset:0x3200
	ds_read_b64_tr_b16 v[98:99], v67 offset:0x3a00
	s_waitcnt lgkmcnt(0)
	v_mfma_f32_32x32x16_bf16 v[18:33], v[68:71], v[84:87], v[18:33]
	ds_read_b64_tr_b16 v[84:85], v67 offset:0x400
	ds_read_b64_tr_b16 v[86:87], v67 offset:0xc00
	v_mfma_f32_32x32x16_bf16 v[18:33], v[72:75], v[88:91], v[18:33]
	ds_read_b64_tr_b16 v[88:89], v67 offset:0x1400
	ds_read_b64_tr_b16 v[90:91], v67 offset:0x1c00
	v_mfma_f32_32x32x16_bf16 v[18:33], v[76:79], v[92:95], v[18:33]
	ds_read_b64_tr_b16 v[92:93], v67 offset:0x2400
	ds_read_b64_tr_b16 v[94:95], v67 offset:0x2c00
	v_mfma_f32_32x32x16_bf16 v[18:33], v[80:83], v[96:99], v[18:33]
	ds_read_b64_tr_b16 v[96:97], v67 offset:0x3400
	ds_read_b64_tr_b16 v[98:99], v67 offset:0x3c00
	s_waitcnt lgkmcnt(0)
	v_mfma_f32_32x32x16_bf16 v[34:49], v[68:71], v[84:87], v[34:49]
	ds_read_b64_tr_b16 v[84:85], v67 offset:0x600
	ds_read_b64_tr_b16 v[86:87], v67 offset:0xe00
	v_mfma_f32_32x32x16_bf16 v[34:49], v[72:75], v[88:91], v[34:49]
	ds_read_b64_tr_b16 v[88:89], v67 offset:0x1600
	ds_read_b64_tr_b16 v[90:91], v67 offset:0x1e00
	v_mfma_f32_32x32x16_bf16 v[34:49], v[76:79], v[92:95], v[34:49]
	ds_read_b64_tr_b16 v[92:93], v67 offset:0x2600
	ds_read_b64_tr_b16 v[94:95], v67 offset:0x2e00
	v_mfma_f32_32x32x16_bf16 v[34:49], v[80:83], v[96:99], v[34:49]
	ds_read_b64_tr_b16 v[96:97], v67 offset:0x3600
	ds_read_b64_tr_b16 v[98:99], v67 offset:0x3e00
	s_waitcnt lgkmcnt(0)
	v_mfma_f32_32x32x16_bf16 v[50:65], v[68:71], v[84:87], v[50:65]
	v_mov_b32_e32 v67, v66
	s_nop 1
	v_permlane32_swap_b32_e32 v66, v67
	v_cmp_gt_u32_e32 vcc, 32, v181
	v_mfma_f32_32x32x16_bf16 v[50:65], v[72:75], v[88:91], v[50:65]
	v_mfma_f32_32x32x16_bf16 v[50:65], v[76:79], v[92:95], v[50:65]
	v_mfma_f32_32x32x16_bf16 v[50:65], v[80:83], v[96:99], v[50:65]
	s_and_saveexec_b64 s[6:7], vcc
	s_cbranch_execz .LBB0_813
	v_add_f32_e32 v66, v66, v67
	v_lshl_add_u32 v67, v180, 2, s10
	ds_write_b32 v67, v66
	s_branch .LBB0_813
